# nt cache hint on the 8 final-norm output stores (268 MB stream never re-read), rest = v028
# speedup vs baseline: 1.0024x; 1.0024x over previous
; #define GAS __attribute__((address_space(1)))
; __device__ __forceinline__ float bf_lo(unsigned w) { return __uint_as_float(w << 16); }
; __device__ __forceinline__ float bf_hi(unsigned w) { return __uint_as_float(w & 0xffff0000u); }
; __global__ void __launch_bounds__(NWAVES * 64, 2) mk_fwd(Args a) {
;     ...
;             for (int m = gw; m < T; m += NGW) { const GAS u32x4* xr = (const GAS u32x4*)(XB0 + (size_t)m * DM) + lane; u32x4 w[4];
; #pragma unroll
;                 for (int j = 0; j < 4; ++j) w[j] = xr[64 * j];
;                 const float rstd = rsqrtf((float)*(const GAS u64_t*)(ssq0 + m) * (SSQ_INV / DM) + EPS);
;                 GAS f32x4* orow = (GAS f32x4*)(a.out + (size_t)m * DM);
; #pragma unroll
;                 for (int j = 0; j < 4; ++j) { const f32x4 v0 = {bf_lo(w[j].x), bf_hi(w[j].x), bf_lo(w[j].y), bf_hi(w[j].y)}, v1 = {bf_lo(w[j].z), bf_hi(w[j].z), bf_lo(w[j].w), bf_hi(w[j].w)};
;                     orow[(lane + 64 * j) * 2] = v0 * rstd * gv[j][0]; orow[(lane + 64 * j) * 2 + 1] = v1 * rstd * gv[j][1]; } }
.LBB0_869:
	global_load_dwordx4 v[36:39], v34, s[8:9]
	global_load_dwordx4 v[40:43], v34, s[8:9] offset:1024
	global_load_dwordx4 v[44:47], v34, s[8:9] offset:2048
	global_load_dwordx4 v[48:51], v34, s[8:9] offset:3072
	global_load_dwordx2 v[52:53], v185, s[6:7]
	s_add_i32 s4, s4, s12
	s_add_u32 s6, s6, s66
	s_addc_u32 s7, s7, s67
	s_add_u32 s8, s8, s62
	s_addc_u32 s9, s9, s63
	s_cmp_lt_i32 s4, 0x8000
	s_waitcnt vmcnt(0)
	v_lshlrev_b32_e32 v54, 16, v36
	v_and_b32_e32 v55, 0xffff0000, v36
	v_lshlrev_b32_e32 v36, 16, v37
	v_and_b32_e32 v37, 0xffff0000, v37
	v_ffbh_u32_e32 v35, v53
	v_min_u32_e32 v35, 32, v35
	v_lshlrev_b64 v[52:53], v35, v[52:53]
	v_min_u32_e32 v52, 1, v52
	v_or_b32_e32 v52, v53, v52
	v_cvt_f32_u32_e32 v52, v52
	v_sub_u32_e32 v35, 32, v35
	v_lshlrev_b32_e32 v56, 16, v38
	v_and_b32_e32 v57, 0xffff0000, v38
	v_ldexp_f32 v35, v52, v35
	v_fmamk_f32 v35, v35, 0x32000000, v232
	v_cmp_gt_f32_e32 vcc, s11, v35
	v_mul_f32_e32 v52, 0x4b800000, v35
	v_lshlrev_b32_e32 v58, 16, v39
	v_cndmask_b32_e32 v35, v35, v52, vcc
	v_rsq_f32_e32 v35, v35
	v_and_b32_e32 v59, 0xffff0000, v39
	v_mul_f32_e32 v52, 0x45800000, v35
	v_cndmask_b32_e32 v52, v35, v52, vcc
	v_pk_mul_f32 v[54:55], v[52:53], v[54:55] op_sel_hi:[0,1]
	v_pk_mul_f32 v[36:37], v[52:53], v[36:37] op_sel_hi:[0,1]
	v_pk_mul_f32 v[38:39], v[36:37], v[6:7]
	v_pk_mul_f32 v[36:37], v[54:55], v[4:5]
	global_store_dwordx4 v[32:33], v[36:39], off offset:-4096 nt
	s_nop 1
	v_pk_mul_f32 v[36:37], v[52:53], v[56:57] op_sel_hi:[0,1]
	v_pk_mul_f32 v[38:39], v[52:53], v[58:59] op_sel_hi:[0,1]
	v_pk_mul_f32 v[38:39], v[38:39], v[2:3]
	v_pk_mul_f32 v[36:37], v[36:37], v[0:1]
	global_store_dwordx4 v[32:33], v[36:39], off offset:-4080 nt
	s_nop 1
	v_lshlrev_b32_e32 v36, 16, v40
	v_and_b32_e32 v37, 0xffff0000, v40
	v_lshlrev_b32_e32 v38, 16, v41
	v_and_b32_e32 v39, 0xffff0000, v41
	v_pk_mul_f32 v[36:37], v[52:53], v[36:37] op_sel_hi:[0,1]
	v_pk_mul_f32 v[38:39], v[52:53], v[38:39] op_sel_hi:[0,1]
	v_lshlrev_b32_e32 v40, 16, v42
	v_and_b32_e32 v41, 0xffff0000, v42
	v_lshlrev_b32_e32 v42, 16, v43
	v_and_b32_e32 v43, 0xffff0000, v43
	v_pk_mul_f32 v[38:39], v[38:39], v[14:15]
	v_pk_mul_f32 v[36:37], v[36:37], v[12:13]
	global_store_dwordx4 v[32:33], v[36:39], off offset:-2048 nt
	s_nop 1
	v_pk_mul_f32 v[36:37], v[52:53], v[40:41] op_sel_hi:[0,1]
	v_pk_mul_f32 v[38:39], v[52:53], v[42:43] op_sel_hi:[0,1]
	v_pk_mul_f32 v[38:39], v[38:39], v[10:11]
	v_pk_mul_f32 v[36:37], v[36:37], v[8:9]
	global_store_dwordx4 v[32:33], v[36:39], off offset:-2032 nt
	v_lshlrev_b32_e32 v40, 16, v46
	v_and_b32_e32 v41, 0xffff0000, v46
	v_lshlrev_b32_e32 v36, 16, v44
	v_and_b32_e32 v37, 0xffff0000, v44
	v_lshlrev_b32_e32 v38, 16, v45
	v_and_b32_e32 v39, 0xffff0000, v45
	v_pk_mul_f32 v[36:37], v[52:53], v[36:37] op_sel_hi:[0,1]
	v_pk_mul_f32 v[38:39], v[52:53], v[38:39] op_sel_hi:[0,1]
	v_lshlrev_b32_e32 v42, 16, v47
	v_and_b32_e32 v43, 0xffff0000, v47
	v_pk_mul_f32 v[38:39], v[38:39], v[18:19]
	v_pk_mul_f32 v[36:37], v[36:37], v[16:17]
	global_store_dwordx4 v[32:33], v[36:39], off nt
	s_nop 1
	v_pk_mul_f32 v[36:37], v[52:53], v[40:41] op_sel_hi:[0,1]
	v_pk_mul_f32 v[38:39], v[52:53], v[42:43] op_sel_hi:[0,1]
	v_pk_mul_f32 v[38:39], v[38:39], v[22:23]
	v_pk_mul_f32 v[36:37], v[36:37], v[20:21]
	global_store_dwordx4 v[32:33], v[36:39], off offset:16 nt
	v_lshlrev_b32_e32 v40, 16, v50
	v_and_b32_e32 v41, 0xffff0000, v50
	v_lshlrev_b32_e32 v36, 16, v48
	v_and_b32_e32 v37, 0xffff0000, v48
	v_lshlrev_b32_e32 v38, 16, v49
	v_and_b32_e32 v39, 0xffff0000, v49
	v_pk_mul_f32 v[36:37], v[52:53], v[36:37] op_sel_hi:[0,1]
	v_pk_mul_f32 v[38:39], v[52:53], v[38:39] op_sel_hi:[0,1]
	v_lshlrev_b32_e32 v42, 16, v51
	v_and_b32_e32 v43, 0xffff0000, v51
	v_pk_mul_f32 v[38:39], v[38:39], v[26:27]
	v_pk_mul_f32 v[36:37], v[36:37], v[24:25]
	global_store_dwordx4 v[32:33], v[36:39], off offset:2048 nt
	s_nop 1
	v_pk_mul_f32 v[36:37], v[52:53], v[40:41] op_sel_hi:[0,1]
	v_pk_mul_f32 v[38:39], v[52:53], v[42:43] op_sel_hi:[0,1]
	v_pk_mul_f32 v[38:39], v[38:39], v[30:31]
	v_pk_mul_f32 v[36:37], v[36:37], v[28:29]
	global_store_dwordx4 v[32:33], v[36:39], off offset:2064 nt
	v_lshl_add_u64 v[32:33], v[32:33], 0, s[72:73]
	s_cbranch_scc1 .LBB0_869
